# attention: ALiBi bias of each 32-key half kept in 32 VGPRs per item and fed as the C operand of the first QK^T MFMA (the separate bias MFMA k-step is gone: 24 instead of 26 MFMAs per wave and KV step)
# speedup vs baseline: 1.0028x; 1.0028x over previous
.LBB0_244:
	v_add_f32_e32 v0, v33, v34
	v_mul_f32_e32 v1, 0x4f800000, v0
	v_cmp_gt_f32_e32 vcc, s80, v0
	s_add_i32 s0, s0, 1
	v_mov_b32_e32 v14, v97
	v_cndmask_b32_e32 v0, v0, v1, vcc
	v_sqrt_f32_e32 v1, v0
	v_mov_b32_e32 v15, v97
	v_mov_b32_e32 v4, v97
	v_mov_b32_e32 v5, v97
	v_add_u32_e32 v2, -1, v1
	v_fma_f32 v3, -v2, v1, v0
	v_cmp_ge_f32_e64 s[20:21], 0, v3
	v_add_u32_e32 v3, 1, v1
	v_mov_b32_e32 v6, v97
	v_cndmask_b32_e64 v2, v1, v2, s[20:21]
	v_fma_f32 v1, -v3, v1, v0
	v_cmp_lt_f32_e64 s[20:21], 0, v1
	v_mov_b32_e32 v7, v97
	v_mov_b32_e32 v8, v97
	v_cndmask_b32_e64 v1, v2, v3, s[20:21]
	v_mul_f32_e32 v2, 0x37800000, v1
	v_cndmask_b32_e32 v1, v1, v2, vcc
	v_cmp_class_f32_e32 vcc, v0, v195
	v_mov_b32_e32 v3, v97
	v_mov_b32_e32 v9, v97
	v_cndmask_b32_e32 v0, v1, v0, vcc
	v_cvt_f32_ubyte0_e32 v1, s0
	s_mov_b32 s0, 0x42fc0000
	v_cmp_lt_f32_e32 vcc, s0, v1
	s_and_b64 s[0:1], vcc, exec
	s_cselect_b32 s0, 0xffffffc0, 0
	v_cndmask_b32_e32 v2, 0, v199, vcc
	v_sub_f32_e32 v1, v2, v1
	v_exp_f32_e32 v1, v1
	v_mul_f32_e32 v160, 0x3f8020c5, v0
	s_lshl_b32 s12, s13, 3
	s_lshl_b32 s14, s13, 1
	v_ldexp_f32 v0, v1, s0
	v_mul_f32_e32 v161, 0x3fb8aa3b, v0
	v_cvt_pk_bf16_f32 v1, v161, 0
	v_lshlrev_b32_e32 v1, 16, v1
	s_mov_b32 s0, 0x3fb8aa3b
	v_fma_f32 v0, v0, s0, -v1
	v_cvt_pk_bf16_f32 v0, v1, v0
	v_cndmask_b32_e64 v96, 0, v0, s[10:11]
	v_lshlrev_b32_e32 v166, 16, v0
	v_and_b32_e32 v167, 0xffff0000, v0
	v_lshrrev_b32_e32 v168, 5, v254
	v_lshlrev_b32_e32 v168, 3, v168
	v_add_u32_e32 v169, 0, v168
	v_cvt_f32_u32_e32 v169, v169
	v_mul_f32_e32 v170, v169, v167
	v_fma_f32 v214, v169, v166, v170
	v_add_u32_e32 v169, 1, v168
	v_cvt_f32_u32_e32 v169, v169
	v_mul_f32_e32 v170, v169, v167
	v_fma_f32 v215, v169, v166, v170
	v_add_u32_e32 v169, 2, v168
	v_cvt_f32_u32_e32 v169, v169
	v_mul_f32_e32 v170, v169, v167
	v_fma_f32 v216, v169, v166, v170
	v_add_u32_e32 v169, 3, v168
	v_cvt_f32_u32_e32 v169, v169
	v_mul_f32_e32 v170, v169, v167
	v_fma_f32 v217, v169, v166, v170
	v_add_u32_e32 v169, 4, v168
	v_cvt_f32_u32_e32 v169, v169
	v_mul_f32_e32 v170, v169, v167
	v_fma_f32 v218, v169, v166, v170
	v_add_u32_e32 v169, 5, v168
	v_cvt_f32_u32_e32 v169, v169
	v_mul_f32_e32 v170, v169, v167
	v_fma_f32 v219, v169, v166, v170
	v_add_u32_e32 v169, 6, v168
	v_cvt_f32_u32_e32 v169, v169
	v_mul_f32_e32 v170, v169, v167
	v_fma_f32 v220, v169, v166, v170
	v_add_u32_e32 v169, 7, v168
	v_cvt_f32_u32_e32 v169, v169
	v_mul_f32_e32 v170, v169, v167
	v_fma_f32 v221, v169, v166, v170
	v_add_u32_e32 v169, 16, v168
	v_cvt_f32_u32_e32 v169, v169
	v_mul_f32_e32 v170, v169, v167
	v_fma_f32 v222, v169, v166, v170
	v_add_u32_e32 v169, 17, v168
	v_cvt_f32_u32_e32 v169, v169
	v_mul_f32_e32 v170, v169, v167
	v_fma_f32 v223, v169, v166, v170
	v_add_u32_e32 v169, 18, v168
	v_cvt_f32_u32_e32 v169, v169
	v_mul_f32_e32 v170, v169, v167
	v_fma_f32 v224, v169, v166, v170
	v_add_u32_e32 v169, 19, v168
	v_cvt_f32_u32_e32 v169, v169
	v_mul_f32_e32 v170, v169, v167
	v_fma_f32 v225, v169, v166, v170
	v_add_u32_e32 v169, 20, v168
	v_cvt_f32_u32_e32 v169, v169
	v_mul_f32_e32 v170, v169, v167
	v_fma_f32 v226, v169, v166, v170
	v_add_u32_e32 v169, 21, v168
	v_cvt_f32_u32_e32 v169, v169
	v_mul_f32_e32 v170, v169, v167
	v_fma_f32 v227, v169, v166, v170
	v_add_u32_e32 v169, 22, v168
	v_cvt_f32_u32_e32 v169, v169
	v_mul_f32_e32 v170, v169, v167
	v_fma_f32 v228, v169, v166, v170
	v_add_u32_e32 v169, 23, v168
	v_cvt_f32_u32_e32 v169, v169
	v_mul_f32_e32 v170, v169, v167
	v_fma_f32 v229, v169, v166, v170
	v_add_u32_e32 v169, 32, v168
	v_cvt_f32_u32_e32 v169, v169
	v_mul_f32_e32 v170, v169, v167
	v_fma_f32 v230, v169, v166, v170
	v_add_u32_e32 v169, 33, v168
	v_cvt_f32_u32_e32 v169, v169
	v_mul_f32_e32 v170, v169, v167
	v_fma_f32 v231, v169, v166, v170
	v_add_u32_e32 v169, 34, v168
	v_cvt_f32_u32_e32 v169, v169
	v_mul_f32_e32 v170, v169, v167
	v_fma_f32 v232, v169, v166, v170
	v_add_u32_e32 v169, 35, v168
	v_cvt_f32_u32_e32 v169, v169
	v_mul_f32_e32 v170, v169, v167
	v_fma_f32 v233, v169, v166, v170
	v_add_u32_e32 v169, 36, v168
	v_cvt_f32_u32_e32 v169, v169
	v_mul_f32_e32 v170, v169, v167
	v_fma_f32 v234, v169, v166, v170
	v_add_u32_e32 v169, 37, v168
	v_cvt_f32_u32_e32 v169, v169
	v_mul_f32_e32 v170, v169, v167
	v_fma_f32 v235, v169, v166, v170
	v_add_u32_e32 v169, 38, v168
	v_cvt_f32_u32_e32 v169, v169
	v_mul_f32_e32 v170, v169, v167
	v_fma_f32 v236, v169, v166, v170
	v_add_u32_e32 v169, 39, v168
	v_cvt_f32_u32_e32 v169, v169
	v_mul_f32_e32 v170, v169, v167
	v_fma_f32 v237, v169, v166, v170
	v_add_u32_e32 v169, 48, v168
	v_cvt_f32_u32_e32 v169, v169
	v_mul_f32_e32 v170, v169, v167
	v_fma_f32 v238, v169, v166, v170
	v_add_u32_e32 v169, 49, v168
	v_cvt_f32_u32_e32 v169, v169
	v_mul_f32_e32 v170, v169, v167
	v_fma_f32 v239, v169, v166, v170
	v_add_u32_e32 v169, 50, v168
	v_cvt_f32_u32_e32 v169, v169
	v_mul_f32_e32 v170, v169, v167
	v_fma_f32 v240, v169, v166, v170
	v_add_u32_e32 v169, 51, v168
	v_cvt_f32_u32_e32 v169, v169
	v_mul_f32_e32 v170, v169, v167
	v_fma_f32 v241, v169, v166, v170
	v_add_u32_e32 v169, 52, v168
	v_cvt_f32_u32_e32 v169, v169
	v_mul_f32_e32 v170, v169, v167
	v_fma_f32 v242, v169, v166, v170
	v_add_u32_e32 v169, 53, v168
	v_cvt_f32_u32_e32 v169, v169
	v_mul_f32_e32 v170, v169, v167
	v_fma_f32 v243, v169, v166, v170
	v_add_u32_e32 v169, 54, v168
	v_cvt_f32_u32_e32 v169, v169
	v_mul_f32_e32 v170, v169, v167
	v_fma_f32 v244, v169, v166, v170
	v_add_u32_e32 v169, 55, v168
	v_cvt_f32_u32_e32 v169, v169
	v_mul_f32_e32 v170, v169, v167
	v_fma_f32 v245, v169, v166, v170
	v_add_f32_e32 v0, v161, v161
	v_readlane_b32 s0, v255, 24
	v_readfirstlane_b32 s68, v0
	s_lshl_b32 s13, s13, 7
	v_mov_b32_e32 v0, v97
	v_mov_b32_e32 v1, v97
	v_mov_b32_e32 v2, v97
	v_mov_b32_e32 v10, v97
	v_mov_b32_e32 v11, v97
	v_mov_b32_e32 v12, v97
	v_mov_b32_e32 v13, v97
	v_mov_b64_e32 v[30:31], v[14:15]
	v_mov_b64_e32 v[46:47], v[14:15]
	v_mov_b64_e32 v[62:63], v[14:15]
	s_mov_b32 s38, 0
	v_mov_b32_e32 v98, v97
	v_mov_b32_e32 v99, v97
	s_add_i32 s39, s39, s0
	s_mov_b32 s69, s68
	s_mov_b32 s70, s68
	s_mov_b32 s71, s68
	s_mov_b32 s81, s68
	s_mov_b32 s83, s68
	s_mov_b32 s84, s68
	s_mov_b32 s89, s68
	s_mov_b32 s90, s68
	s_mov_b32 s91, s68
	s_mov_b32 s92, s68
	s_mov_b32 s93, s68
	s_mov_b32 s94, s68
	s_mov_b32 s95, s68
	s_mov_b32 s96, s68
	s_mov_b32 s97, s68
	s_mov_b32 s98, s68
	s_mov_b32 s99, s68
	s_mov_b32 s0, s68
	s_mov_b32 s1, s68
	s_mov_b32 s73, s68
	s_mov_b32 s74, s68
	s_mov_b32 s85, s68
	s_mov_b32 s87, s68
	s_mov_b32 s86, s68
	s_mov_b32 s36, s68
	s_mov_b32 s37, s68
	s_mov_b32 s44, s68
	s_mov_b32 s45, s68
	s_mov_b32 s46, s68
	s_mov_b32 s47, s68
	s_mov_b32 s88, s68
	s_sub_i32 s12, 0x1bdf8, s12
	s_add_i32 s75, s14, 0xffffff81
	s_add_i32 s64, s14, 0xffffff80
	s_sub_i32 s65, 0, s13
	s_sub_i32 s13, 0, s14
	v_mov_b32_e32 v162, 0xf149f2ca
	v_mov_b32_e32 v153, 0
	s_mov_b32 s14, 2
	v_mov_b32_e32 v164, 0
	s_mov_b32 s15, 0
	v_mov_b32_e32 v155, v149
	v_mov_b64_e32 v[28:29], v[12:13]
	v_mov_b64_e32 v[26:27], v[10:11]
	v_mov_b64_e32 v[24:25], v[8:9]
	v_mov_b64_e32 v[22:23], v[6:7]
	v_mov_b64_e32 v[20:21], v[4:5]
	v_mov_b64_e32 v[18:19], v[2:3]
	v_mov_b64_e32 v[16:17], v[0:1]
	v_mov_b64_e32 v[44:45], v[12:13]
	v_mov_b64_e32 v[42:43], v[10:11]
	v_mov_b64_e32 v[40:41], v[8:9]
	v_mov_b64_e32 v[38:39], v[6:7]
	v_mov_b64_e32 v[36:37], v[4:5]
	v_mov_b64_e32 v[34:35], v[2:3]
	v_mov_b64_e32 v[32:33], v[0:1]
	v_mov_b64_e32 v[60:61], v[12:13]
	v_mov_b64_e32 v[58:59], v[10:11]
	v_mov_b64_e32 v[56:57], v[8:9]
	v_mov_b64_e32 v[54:55], v[6:7]
	v_mov_b64_e32 v[52:53], v[4:5]
	v_mov_b64_e32 v[50:51], v[2:3]
	v_mov_b64_e32 v[48:49], v[0:1]
	s_mov_b32 s16, 0
	s_add_i32 s17, s78, s12
	v_mov_b32_e32 v211, s17
	ds_read_b32 v210, v211
	v_mov_b32_e32 v178, v193
	ds_read_b128 v[246:249], v178
	ds_read_b128 v[250:253], v178 offset:32
	ds_read_b128 v[200:203], v178 offset:64
	ds_read_b128 v[204:207], v178 offset:96
	ds_read_b128 v[100:103], v178 offset:8704
	ds_read_b128 v[104:107], v178 offset:8736
	s_waitcnt lgkmcnt(5)
	v_mfma_f32_32x32x16_bf16 v[80:95], v[246:249], v[108:111], v[214:229]
	ds_read_b128 v[246:249], v178 offset:8768
	s_waitcnt lgkmcnt(5)
	v_mfma_f32_32x32x16_bf16 v[80:95], v[250:253], v[112:115], v[80:95]
	ds_read_b128 v[250:253], v178 offset:8800
	s_waitcnt lgkmcnt(5)
	v_mfma_f32_32x32x16_bf16 v[80:95], v[200:203], v[116:119], v[80:95]
	s_waitcnt lgkmcnt(4)
	v_mfma_f32_32x32x16_bf16 v[80:95], v[204:207], v[120:123], v[80:95]
	s_waitcnt lgkmcnt(3)
	v_mfma_f32_32x32x16_bf16 v[64:79], v[100:103], v[108:111], v[230:245]
	s_waitcnt lgkmcnt(2)
	v_mfma_f32_32x32x16_bf16 v[64:79], v[104:107], v[112:115], v[64:79]
	s_waitcnt lgkmcnt(1)
	v_mfma_f32_32x32x16_bf16 v[64:79], v[246:249], v[116:119], v[64:79]
	s_waitcnt lgkmcnt(0)
	v_mfma_f32_32x32x16_bf16 v[64:79], v[250:253], v[120:123], v[64:79]

.LBB0_254:
	s_and_b64 vcc, exec, s[20:21]
	s_barrier
	s_min_u32 s17, s4, 3
	s_lshl_b32 s17, s17, 6
	s_sub_i32 s17, s65, s17
	s_add_i32 s17, s15, s17
	s_mul_i32 s18, s14, 0x4400
	s_mul_i32 s19, s14, 0x5000
	s_add_i32 s40, s17, 0x1fc0
	v_add_u32_e32 v168, s18, v146
	v_add_u32_e32 v169, s19, v148
	s_lshl_b64 s[18:19], s[40:41], 9
	s_add_i32 s40, s17, 0x1fe0
	s_waitcnt vmcnt(3)
	ds_write_b128 v168, v[128:131]
	s_waitcnt vmcnt(2)
	ds_write_b128 v169, v[124:127] offset:52224
	s_waitcnt vmcnt(1)
	ds_write_b128 v168, v[132:135] offset:8704
	s_waitcnt vmcnt(0)
	ds_write_b128 v169, v[136:139] offset:62464
	v_lshl_add_u64 v[170:171], v[158:159], 0, s[18:19]
	s_lshl_b64 s[18:19], s[40:41], 9
	global_load_dwordx4 v[128:131], v[170:171], off
	global_load_dwordx4 v[124:127], v[170:171], off offset:256
	v_lshl_add_u64 v[170:171], v[158:159], 0, s[18:19]
	global_load_dwordx4 v[132:135], v[170:171], off
	global_load_dwordx4 v[136:139], v[170:171], off offset:256
	s_add_i32 s17, s12, 0xfffe4404
	s_and_b32 s17, s17, 4
	s_xor_b32 s40, s17, 4
	s_and_saveexec_b64 s[20:21], s[6:7]
	s_lshl_b32 s18, s40, 2
	s_add_i32 s18, s77, s18
	v_mov_b32_e32 v168, s18
	ds_write_b32 v168, v164
	s_or_b64 exec, exec, s[20:21]
	s_cbranch_vccnz .LBB0_256
	s_mul_i32 s17, s16, 0x5000
	v_add3_u32 v166, v192, s17, v189
	v_add_u32_e32 v167, 0xcc00, v166
	s_waitcnt lgkmcnt(2)
	ds_read_b64_tr_b16 v[246:247], v166 offset:52224
	ds_read_b64_tr_b16 v[248:249], v166 offset:53504
	ds_read_b64_tr_b16 v[250:251], v166 offset:52288
	ds_read_b64_tr_b16 v[252:253], v166 offset:53568
	ds_read_b64_tr_b16 v[200:201], v166 offset:52352
	ds_read_b64_tr_b16 v[202:203], v166 offset:53632
	ds_read_b64_tr_b16 v[204:205], v166 offset:52416
	ds_read_b64_tr_b16 v[206:207], v166 offset:53696
	ds_read_b64_tr_b16 v[100:101], v166 offset:57344
	ds_read_b64_tr_b16 v[102:103], v166 offset:58624
	ds_read_b64_tr_b16 v[104:105], v166 offset:57408
	ds_read_b64_tr_b16 v[106:107], v166 offset:58688
	v_sub_f32_e32 v88, v88, v162
	v_sub_f32_e32 v89, v89, v162
	v_sub_f32_e32 v90, v90, v162
	v_sub_f32_e32 v91, v91, v162
	v_sub_f32_e32 v92, v92, v162
	v_sub_f32_e32 v93, v93, v162
	v_sub_f32_e32 v94, v94, v162
	v_sub_f32_e32 v95, v95, v162
	s_waitcnt lgkmcnt(10)
	v_mfma_f32_32x32x16_bf16 v[48:63], v[246:249], v[80:83], v[48:63]
	v_exp_f32_e32 v88, v88
	v_exp_f32_e32 v89, v89
	v_exp_f32_e32 v90, v90
	v_exp_f32_e32 v91, v91
	v_exp_f32_e32 v92, v92
	v_exp_f32_e32 v93, v93
	v_exp_f32_e32 v94, v94
	ds_read_b64_tr_b16 v[246:247], v166 offset:57472
	ds_read_b64_tr_b16 v[248:249], v166 offset:58752
	s_waitcnt lgkmcnt(10)
	v_mfma_f32_32x32x16_bf16 v[32:47], v[250:253], v[80:83], v[32:47]
	v_exp_f32_e32 v95, v95
	v_add_f32_e32 v153, v153, v88
	v_add_f32_e32 v153, v153, v89
	v_add_f32_e32 v153, v153, v90
	v_add_f32_e32 v153, v153, v91
	v_add_f32_e32 v153, v153, v92
	ds_read_b64_tr_b16 v[250:251], v166 offset:57536
	ds_read_b64_tr_b16 v[252:253], v166 offset:58816
	s_waitcnt lgkmcnt(10)
	v_mfma_f32_32x32x16_bf16 v[16:31], v[200:203], v[80:83], v[16:31]
	v_add_f32_e32 v153, v153, v93
	v_add_f32_e32 v153, v153, v94
	v_add_f32_e32 v153, v153, v95
	v_cvt_pk_bf16_f32 v88, v88, v89
	v_cvt_pk_bf16_f32 v89, v90, v91
	v_cvt_pk_bf16_f32 v90, v92, v93
	ds_read_b64_tr_b16 v[200:201], v166 offset:62464
	ds_read_b64_tr_b16 v[202:203], v166 offset:63744
	s_waitcnt lgkmcnt(10)
	v_mfma_f32_32x32x16_bf16 v[0:15], v[204:207], v[80:83], v[0:15]
	v_cvt_pk_bf16_f32 v91, v94, v95
	v_sub_f32_e32 v64, v64, v162
	v_sub_f32_e32 v65, v65, v162
	v_sub_f32_e32 v66, v66, v162
	v_sub_f32_e32 v67, v67, v162
	v_sub_f32_e32 v68, v68, v162
	v_sub_f32_e32 v69, v69, v162
	ds_read_b64_tr_b16 v[204:205], v166 offset:62528
	ds_read_b64_tr_b16 v[206:207], v166 offset:63808
	s_waitcnt lgkmcnt(10)
	v_mfma_f32_32x32x16_bf16 v[48:63], v[100:103], v[88:91], v[48:63]
	v_sub_f32_e32 v70, v70, v162
	v_sub_f32_e32 v71, v71, v162
	v_exp_f32_e32 v64, v64
	v_exp_f32_e32 v65, v65
	v_exp_f32_e32 v66, v66
	v_exp_f32_e32 v67, v67
	ds_read_b64_tr_b16 v[100:101], v166 offset:62592
	ds_read_b64_tr_b16 v[102:103], v166 offset:63872
	s_waitcnt lgkmcnt(10)
	v_mfma_f32_32x32x16_bf16 v[32:47], v[104:107], v[88:91], v[32:47]
	v_exp_f32_e32 v68, v68
	v_exp_f32_e32 v69, v69
	v_exp_f32_e32 v70, v70
	v_exp_f32_e32 v71, v71
	v_add_f32_e32 v153, v153, v64
	v_add_f32_e32 v153, v153, v65
	ds_read_b64_tr_b16 v[104:105], v166 offset:62656
	ds_read_b64_tr_b16 v[106:107], v166 offset:63936
	s_waitcnt lgkmcnt(10)
	v_mfma_f32_32x32x16_bf16 v[16:31], v[246:249], v[88:91], v[16:31]
	v_add_f32_e32 v153, v153, v66
	v_add_f32_e32 v153, v153, v67
	v_add_f32_e32 v153, v153, v68
	v_add_f32_e32 v153, v153, v69
	v_add_f32_e32 v153, v153, v70
	v_add_f32_e32 v153, v153, v71
	v_cvt_pk_bf16_f32 v64, v64, v65
	ds_read_b64_tr_b16 v[246:247], v167 offset:15360
	ds_read_b64_tr_b16 v[248:249], v167 offset:16640
	s_waitcnt lgkmcnt(10)
	v_mfma_f32_32x32x16_bf16 v[0:15], v[250:253], v[88:91], v[0:15]
	v_cvt_pk_bf16_f32 v65, v66, v67
	v_cvt_pk_bf16_f32 v66, v68, v69
	v_cvt_pk_bf16_f32 v67, v70, v71
	v_sub_f32_e32 v72, v72, v162
	v_sub_f32_e32 v73, v73, v162
	v_sub_f32_e32 v74, v74, v162
	ds_read_b64_tr_b16 v[250:251], v167 offset:15424
	ds_read_b64_tr_b16 v[252:253], v167 offset:16704
	s_waitcnt lgkmcnt(10)
	v_mfma_f32_32x32x16_bf16 v[48:63], v[200:203], v[64:67], v[48:63]
	v_sub_f32_e32 v75, v75, v162
	v_sub_f32_e32 v76, v76, v162
	v_sub_f32_e32 v77, v77, v162
	v_sub_f32_e32 v78, v78, v162
	v_sub_f32_e32 v79, v79, v162
	v_exp_f32_e32 v72, v72
	ds_read_b64_tr_b16 v[200:201], v167 offset:15488
	ds_read_b64_tr_b16 v[202:203], v167 offset:16768
	s_waitcnt lgkmcnt(10)
	v_mfma_f32_32x32x16_bf16 v[32:47], v[204:207], v[64:67], v[32:47]
	v_exp_f32_e32 v73, v73
	v_exp_f32_e32 v74, v74
	v_exp_f32_e32 v75, v75
	v_exp_f32_e32 v76, v76
	v_exp_f32_e32 v77, v77
	v_exp_f32_e32 v78, v78
	v_exp_f32_e32 v79, v79
	ds_read_b64_tr_b16 v[204:205], v167 offset:15552
	ds_read_b64_tr_b16 v[206:207], v167 offset:16832
	s_waitcnt lgkmcnt(10)
	v_mfma_f32_32x32x16_bf16 v[16:31], v[100:103], v[64:67], v[16:31]
	v_add_f32_e32 v153, v153, v72
	v_add_f32_e32 v153, v153, v73
	v_add_f32_e32 v153, v153, v74
	v_add_f32_e32 v153, v153, v75
	v_add_f32_e32 v153, v153, v76
	v_add_f32_e32 v153, v153, v77
	s_waitcnt lgkmcnt(8)
	v_mfma_f32_32x32x16_bf16 v[0:15], v[104:107], v[64:67], v[0:15]
	v_add_f32_e32 v153, v153, v78
	v_add_f32_e32 v153, v153, v79
	v_cvt_pk_bf16_f32 v72, v72, v73
	v_cvt_pk_bf16_f32 v73, v74, v75
	v_cvt_pk_bf16_f32 v74, v76, v77
	v_cvt_pk_bf16_f32 v75, v78, v79
	s_nop 0
	s_waitcnt lgkmcnt(6)
	v_mfma_f32_32x32x16_bf16 v[48:63], v[246:249], v[72:75], v[48:63]
	s_waitcnt lgkmcnt(4)
	v_mfma_f32_32x32x16_bf16 v[32:47], v[250:253], v[72:75], v[32:47]
	s_waitcnt lgkmcnt(2)
	v_mfma_f32_32x32x16_bf16 v[16:31], v[200:203], v[72:75], v[16:31]
	s_waitcnt lgkmcnt(0)
	v_mfma_f32_32x32x16_bf16 v[0:15], v[204:207], v[72:75], v[0:15]
.LBB0_256:
	s_add_i32 s17, s78, s12
	s_add_i32 s17, s17, -4
	v_mov_b32_e32 v211, s17
	ds_read_b32 v210, v211
	s_add_i32 s17, s16, 1
	s_cmp_lg_u32 s16, 2
	s_cselect_b32 s17, s17, 0
	s_mul_i32 s17, s17, 0x4400
	v_add_u32_e32 v178, s17, v193
	ds_read_b128 v[246:249], v178
	ds_read_b128 v[250:253], v178 offset:32
	ds_read_b128 v[200:203], v178 offset:64
	ds_read_b128 v[204:207], v178 offset:96
	ds_read_b128 v[100:103], v178 offset:8704
	ds_read_b128 v[104:107], v178 offset:8736
	s_add_i32 s17, s12, 0xfffe4404
	s_and_b32 s17, s17, 4
	s_xor_b32 s40, s17, 4
	s_lshl_b32 s18, s40, 2
	s_add_i32 s18, s18, 0x1c040
	v_mov_b32_e32 v176, s18
	s_lshl_b32 s17, s17, 2
	s_add_i32 s17, s17, 0x1c060
	v_mov_b32_e32 v177, s17
	s_waitcnt lgkmcnt(7)
	s_barrier
	ds_read_b128 v[168:171], v176
	ds_read_b128 v[172:175], v177
	s_waitcnt lgkmcnt(7)
	v_mfma_f32_32x32x16_bf16 v[80:95], v[246:249], v[108:111], v[214:229]
	ds_read_b128 v[246:249], v178 offset:8768
	s_waitcnt lgkmcnt(7)
	v_mfma_f32_32x32x16_bf16 v[80:95], v[250:253], v[112:115], v[80:95]
	ds_read_b128 v[250:253], v178 offset:8800
	s_waitcnt lgkmcnt(7)
	v_mfma_f32_32x32x16_bf16 v[80:95], v[200:203], v[116:119], v[80:95]
	s_waitcnt lgkmcnt(6)
	v_mfma_f32_32x32x16_bf16 v[80:95], v[204:207], v[120:123], v[80:95]
	s_waitcnt lgkmcnt(5)
	v_mfma_f32_32x32x16_bf16 v[64:79], v[100:103], v[108:111], v[230:245]
	s_waitcnt lgkmcnt(4)
	v_mfma_f32_32x32x16_bf16 v[64:79], v[104:107], v[112:115], v[64:79]
	s_waitcnt lgkmcnt(1)
	v_mfma_f32_32x32x16_bf16 v[64:79], v[246:249], v[116:119], v[64:79]
	s_waitcnt lgkmcnt(0)
	v_mfma_f32_32x32x16_bf16 v[64:79], v[250:253], v[120:123], v[64:79]
	s_waitcnt lgkmcnt(0)
	v_and_b32_e32 v168, v168, v169
	v_and_b32_e32 v168, v168, v170
	v_and_b32_e32 v168, v168, v171
	v_and_b32_e32 v168, v168, v172
	v_and_b32_e32 v168, v168, v173
	v_and_b32_e32 v168, v168, v174
	v_and_b32_e32 v168, v168, v175
	v_cmp_ne_u32_e32 vcc, 0, v168
	s_cbranch_vccz .LBB0_260
	s_branch .LBB0_262
